# attention: fixed rigorous softmax reference folded into the accumulator init, tile LDS operands requested up front, key cumsums staged once per tile by wave 0, nt policy on the K/V tile DMA
# speedup vs baseline: 1.0062x; 1.0062x over previous
; DI void fox_attn_blk(const Params& P, unsigned char* lds, LAS unsigned char* ldsl, int tid, int G, float PRUNE, int pir) {
;     ...
;         const int QB0 = grp * 8, qb = QB0 + wave, t0 = qb * 32, nq = qb >> 1;
;         bf16x8 qf[4];
; #pragma unroll
;         for (int ks = 0; ks < 4; ++ks) qf[ks] = *(const bf16x8*)(QN + (size_t)(t0 + r32) * 512 + h * 64 + 16 * ks + 8 * hi);
;         const float cq = CLh[t0 + r32];
;         const float cq0 = __uint_as_float(__builtin_amdgcn_readfirstlane(__float_as_uint(CLh[t0])));
;         float offv; int nvalid;
;         { const int cn = nq - 1 - lane; float pre = cn >= 0 ? CTh[cn] : 0.f;
;           const int kt = qb - 1 - lane; const float clen = kt >= 0 ? CLh[32 * kt + 31] : 0.f;
.LBB0_734:
	v_mov_b32_e32 v118, 0xc19d1eb8
	v_fmac_f32_e32 v118, 0.5, v205
	s_lshl_b32 s33, s3, 3
	v_add_u32_e32 v88, s33, v1
	v_lshlrev_b32_e32 v130, 5, v88
	v_or_b32_e32 v2, v130, v165
	v_ashrrev_i32_e32 v3, 31, v2
	v_lshlrev_b64 v[4:5], 10, v[2:3]
	v_lshl_add_u64 v[84:85], v[174:175], 0, v[4:5]
	global_load_dwordx4 v[50:53], v[84:85], off
	global_load_dwordx4 v[54:57], v[84:85], off offset:32
	v_lshl_add_u64 v[86:87], v[2:3], 2, s[64:65]
	v_ashrrev_i32_e32 v131, 31, v130
	v_lshl_add_u64 v[82:83], v[130:131], 2, s[64:65]
	global_load_dword v90, v[86:87], off
	global_load_dword v4, v[82:83], off
	global_load_dwordx4 v[58:61], v[84:85], off offset:64
	global_load_dwordx4 v[62:65], v[84:85], off offset:96
	v_ashrrev_i32_e32 v5, 1, v88
	v_add_u32_e32 v89, -1, v5
	v_sub_u32_e32 v170, v89, v163
	v_cmp_lt_i32_e64 s[54:55], -1, v170
	v_mov_b32_e32 v6, v171
	s_waitcnt vmcnt(0)
	v_readfirstlane_b32 s2, v4
	s_and_saveexec_b64 s[0:1], s[54:55]
	s_cbranch_execz .LBB0_736
	v_lshl_add_u64 v[4:5], v[170:171], 2, s[68:69]
	global_load_dword v6, v[4:5], off

; #define BLK_BAR() asm volatile("s_waitcnt lgkmcnt(0)\n\ts_barrier" ::: "memory")
; DI void fox_attn_blk(const Params& P, unsigned char* lds, LAS unsigned char* ldsl, int tid, int G, float PRUNE, int pir) {
;     ...
;         BLK_BAR();
;         int nvmax = 0;
; #pragma unroll
;         for (int w_ = 0; w_ < 8; ++w_) { const int v_ = nvs[w_]; nvmax = v_ > nvmax ? v_ : nvmax; }
;         nvmax = __builtin_amdgcn_readfirstlane(nvmax);
;         if (nvmax >= 56) {
;             BLK_BAR();
;             fox_attn_unit(P, tid, h, qb, PRUNE, pir);
;             continue; }
;     ...
;         for (int j_ = 0; j_ < 11; ++j_) DMA_TILE(QB0 + 7 - j_);
.LBB0_740:
	s_or_b64 exec, exec, s[0:1]
	s_cmp_lg_u32 s60, -1
	s_cselect_b32 s0, s60, 0
	v_lshlrev_b64 v[194:195], 9, v[2:3]
	s_cselect_b32 s1, s61, 0
	v_mov_b32_e32 v2, s0
	s_add_i32 s0, 0, 0x1e004
	s_cmp_lg_u32 s0, -1
	s_waitcnt lgkmcnt(0)
	s_barrier
	v_mov_b32_e32 v3, s1
	s_cselect_b32 s0, s0, 0
	flat_load_dword v4, v[2:3] sc0 sc1
	s_waitcnt vmcnt(0)
	s_cselect_b32 s1, s61, 0
	v_mov_b32_e32 v2, s0
	s_add_i32 s0, 0, 0x1e008
	s_cmp_lg_u32 s0, -1
	v_mov_b32_e32 v3, s1
	s_cselect_b32 s0, s0, 0
	s_cselect_b32 s1, s61, 0
	flat_load_dword v5, v[2:3] sc0 sc1
	s_waitcnt vmcnt(0)
	v_mov_b32_e32 v2, s0
	v_mov_b32_e32 v3, s1
	flat_load_dword v2, v[2:3] sc0 sc1
	s_waitcnt vmcnt(0)
	s_add_i32 s0, 0, 0x1e00c
	s_cmp_lg_u32 s0, -1
	s_cselect_b32 s0, s0, 0
	s_cselect_b32 s1, s61, 0
	v_mov_b32_e32 v3, s1
	v_or_b32_e32 v194, s9, v194
	s_waitcnt lgkmcnt(0)
	v_max3_i32 v4, v4, v5, v2
	v_mov_b32_e32 v2, s0
	s_add_i32 s0, 0, 0x1e010
	s_cmp_lg_u32 s0, -1
	s_cselect_b32 s0, s0, 0
	s_cselect_b32 s1, s61, 0
	flat_load_dword v5, v[2:3] sc0 sc1
	s_waitcnt vmcnt(0)
	v_mov_b32_e32 v2, s0
	v_mov_b32_e32 v3, s1
	flat_load_dword v2, v[2:3] sc0 sc1
	s_waitcnt vmcnt(0)
	s_add_i32 s0, 0, 0x1e014
	s_cmp_lg_u32 s0, -1
	s_cselect_b32 s0, s0, 0
	s_cselect_b32 s1, s61, 0
	v_mov_b32_e32 v3, s1
	s_waitcnt lgkmcnt(0)
	v_max3_i32 v4, v4, v5, v2
	v_mov_b32_e32 v2, s0
	s_add_i32 s0, 0, 0x1e018
	s_cmp_lg_u32 s0, -1
	s_cselect_b32 s0, s0, 0
	s_cselect_b32 s1, s61, 0
	flat_load_dword v5, v[2:3] sc0 sc1
	s_waitcnt vmcnt(0)
	v_mov_b32_e32 v2, s0
	v_mov_b32_e32 v3, s1
	flat_load_dword v2, v[2:3] sc0 sc1
	s_waitcnt vmcnt(0)
	s_add_i32 s0, 0, 0x1e01c
	s_cmp_lg_u32 s0, -1
	s_cselect_b32 s0, s0, 0
	s_cselect_b32 s1, s61, 0
	v_mov_b32_e32 v3, s1
	s_waitcnt lgkmcnt(0)
	v_max3_i32 v4, v4, v5, v2
	v_mov_b32_e32 v2, s0
	flat_load_dword v2, v[2:3] sc0 sc1
	s_waitcnt vmcnt(0)
	s_mov_b64 s[0:1], -1
	s_waitcnt lgkmcnt(0)
	v_max3_i32 v2, v4, v2, 0
	s_nop 0
	v_readfirstlane_b32 s5, v2
	s_cmp_gt_i32 s5, 55
	s_cbranch_scc1 .LBB0_765
	v_lshlrev_b64 v[254:255], 1, v[194:195]
	v_lshl_add_u64 v[254:255], v[186:187], 0, v[254:255]
	global_load_dwordx2 v[240:241], v[254:255], off
	global_load_dwordx2 v[242:243], v[254:255], off offset:16
	global_load_dwordx2 v[244:245], v[254:255], off offset:32
	global_load_dwordx2 v[246:247], v[254:255], off offset:48
	global_load_dwordx2 v[248:249], v[254:255], off offset:64
	global_load_dwordx2 v[250:251], v[254:255], off offset:80
	global_load_dwordx2 v[252:253], v[254:255], off offset:96
	global_load_dwordx2 v[254:255], v[254:255], off offset:112
	s_or_b32 s0, s33, 7
	s_max_i32 s2, s0, 0
	s_add_i32 s0, s33, 0x7f
	s_mul_hi_i32 s1, s0, 0x2aaaaaab
	s_lshr_b32 s56, s1, 31
	s_lshr_b32 s1, s1, 1
	s_add_i32 s1, s1, s56
	s_mul_i32 s1, s1, 12
	s_sub_i32 s56, s0, s1
	v_mad_u64_u32 v[2:3], s[0:1], v168, s2, 0
	s_mulk_i32 s56, 0x2800
	s_add_i32 s0, s56, 0
	v_lshl_add_u64 v[2:3], v[2:3], 1, v[172:173]
	s_add_i32 m0, s0, s84
	s_add_i32 s0, s0, s85
	global_load_lds_dwordx4 v[2:3], off nt
	s_add_i32 m0, s0, 0x2000
	s_or_b32 s0, s33, 6
	s_lshl_b32 s62, s2, 5
	s_max_i32 s2, s0, 0
	s_add_i32 s0, s33, 0x7e
	s_mul_hi_i32 s1, s0, 0x2aaaaaab
	s_lshr_b32 s56, s1, 31
	s_lshr_b32 s1, s1, 1
	s_add_i32 s1, s1, s56
	s_mul_i32 s1, s1, 12
	v_lshl_add_u64 v[2:3], s[62:63], 2, v[166:167]
	s_sub_i32 s56, s0, s1
	s_cmp_lg_u32 s84, 0
	s_cbranch_scc1 .Lcl_0
	global_load_lds_dword v[2:3], off
.Lcl_0:
	v_mad_u64_u32 v[2:3], s[0:1], v168, s2, 0
	s_mulk_i32 s56, 0x2800
	s_add_i32 s0, s56, 0
	v_lshl_add_u64 v[2:3], v[2:3], 1, v[172:173]
	s_add_i32 m0, s0, s84
	s_add_i32 s0, s0, s85
	global_load_lds_dwordx4 v[2:3], off nt
	s_add_i32 m0, s0, 0x2000
	s_or_b32 s0, s33, 5
	s_lshl_b32 s62, s2, 5
	s_max_i32 s2, s0, 0
	s_add_i32 s0, s33, 0x7d
	s_mul_hi_i32 s1, s0, 0x2aaaaaab
	s_lshr_b32 s56, s1, 31
	s_lshr_b32 s1, s1, 1
	s_add_i32 s1, s1, s56
	s_mul_i32 s1, s1, 12
	v_lshl_add_u64 v[2:3], s[62:63], 2, v[166:167]
	s_sub_i32 s56, s0, s1
	s_cmp_lg_u32 s84, 0
	s_cbranch_scc1 .Lcl_1
	global_load_lds_dword v[2:3], off
.Lcl_1:
	v_mad_u64_u32 v[2:3], s[0:1], v168, s2, 0
	s_mulk_i32 s56, 0x2800
	s_add_i32 s0, s56, 0
	v_lshl_add_u64 v[2:3], v[2:3], 1, v[172:173]
	s_add_i32 m0, s0, s84
	s_add_i32 s0, s0, s85
	global_load_lds_dwordx4 v[2:3], off nt
	s_add_i32 m0, s0, 0x2000
	s_or_b32 s0, s33, 4
	s_lshl_b32 s62, s2, 5
	s_max_i32 s2, s0, 0
	s_add_i32 s0, s33, 0x7c
	s_mul_hi_i32 s1, s0, 0x2aaaaaab
	s_lshr_b32 s56, s1, 31
	s_lshr_b32 s1, s1, 1
	s_add_i32 s1, s1, s56
	s_mul_i32 s1, s1, 12
	v_lshl_add_u64 v[2:3], s[62:63], 2, v[166:167]
	s_sub_i32 s56, s0, s1
	s_cmp_lg_u32 s84, 0
	s_cbranch_scc1 .Lcl_2
	global_load_lds_dword v[2:3], off
.Lcl_2:
	v_mad_u64_u32 v[2:3], s[0:1], v168, s2, 0
	s_mulk_i32 s56, 0x2800
	s_add_i32 s0, s56, 0
	v_lshl_add_u64 v[2:3], v[2:3], 1, v[172:173]
	s_add_i32 m0, s0, s84
	s_add_i32 s0, s0, s85
	global_load_lds_dwordx4 v[2:3], off nt
	s_add_i32 m0, s0, 0x2000
	s_or_b32 s0, s33, 3
	s_lshl_b32 s62, s2, 5
	s_max_i32 s2, s0, 0
	s_add_i32 s0, s33, 0x7b
	s_mul_hi_i32 s1, s0, 0x2aaaaaab
	s_lshr_b32 s56, s1, 31
	s_lshr_b32 s1, s1, 1
	s_add_i32 s1, s1, s56
	s_mul_i32 s1, s1, 12
	v_lshl_add_u64 v[2:3], s[62:63], 2, v[166:167]
	s_sub_i32 s56, s0, s1
	s_cmp_lg_u32 s84, 0
	s_cbranch_scc1 .Lcl_3
	global_load_lds_dword v[2:3], off
.Lcl_3:
	v_mad_u64_u32 v[2:3], s[0:1], v168, s2, 0
	s_mulk_i32 s56, 0x2800
	s_add_i32 s0, s56, 0
	v_lshl_add_u64 v[2:3], v[2:3], 1, v[172:173]
	s_add_i32 m0, s0, s84
	s_add_i32 s0, s0, s85
	global_load_lds_dwordx4 v[2:3], off nt
	s_add_i32 m0, s0, 0x2000
	s_or_b32 s0, s33, 2
	s_lshl_b32 s62, s2, 5
	s_max_i32 s2, s0, 0
	s_add_i32 s0, s33, 0x7a
	s_mul_hi_i32 s1, s0, 0x2aaaaaab
	s_lshr_b32 s56, s1, 31
	s_lshr_b32 s1, s1, 1
	s_add_i32 s1, s1, s56
	s_mul_i32 s1, s1, 12
	v_lshl_add_u64 v[2:3], s[62:63], 2, v[166:167]
	s_sub_i32 s56, s0, s1
	s_cmp_lg_u32 s84, 0
	s_cbranch_scc1 .Lcl_4
	global_load_lds_dword v[2:3], off
; #define BLK_BAR() asm volatile("s_waitcnt lgkmcnt(0)\n\ts_barrier" ::: "memory")
; DI void fox_attn_blk(const Params& P, unsigned char* lds, LAS unsigned char* ldsl, int tid, int G, float PRUNE, int pir) {
;     ...
;         for (int j_ = 0; j_ < 11; ++j_) DMA_TILE(QB0 + 7 - j_);
;         asm volatile("s_waitcnt vmcnt(6)" ::: "memory");
;         float mrun = -INFINITY, lsum = 0.f;
;         f32x16 oT[2];
; #pragma unroll
;         for (int i = 0; i < 16; ++i) { oT[0][i] = 0.f; oT[1][i] = 0.f; }
;         BLK_BAR();
;     ...
;             DMA_TILE(QB0 - it - 4);
.Lcl_4:
	v_mad_u64_u32 v[2:3], s[0:1], v168, s2, 0
	s_mulk_i32 s56, 0x2800
	s_add_i32 s0, s56, 0
	v_lshl_add_u64 v[2:3], v[2:3], 1, v[172:173]
	s_add_i32 m0, s0, s84
	s_add_i32 s0, s0, s85
	global_load_lds_dwordx4 v[2:3], off nt
	s_add_i32 m0, s0, 0x2000
	s_or_b32 s0, s33, 1
	s_lshl_b32 s62, s2, 5
	s_max_i32 s2, s0, 0
	s_add_i32 s0, s33, 0x79
	s_mul_hi_i32 s1, s0, 0x2aaaaaab
	s_lshr_b32 s56, s1, 31
	s_lshr_b32 s1, s1, 1
	s_add_i32 s1, s1, s56
	s_mul_i32 s1, s1, 12
	v_lshl_add_u64 v[2:3], s[62:63], 2, v[166:167]
	s_sub_i32 s56, s0, s1
	s_cmp_lg_u32 s84, 0
	s_cbranch_scc1 .Lcl_5
	global_load_lds_dword v[2:3], off
.Lcl_5:
	v_mad_u64_u32 v[2:3], s[0:1], v168, s2, 0
	s_mulk_i32 s56, 0x2800
	s_add_i32 s0, s56, 0
	v_lshl_add_u64 v[2:3], v[2:3], 1, v[172:173]
	s_add_i32 m0, s0, s84
	s_add_i32 s0, s0, s85
	global_load_lds_dwordx4 v[2:3], off nt
	s_add_i32 m0, s0, 0x2000
	s_add_i32 s0, s33, 0x78
	s_mul_hi_i32 s1, s0, 0x2aaaaaab
	s_lshr_b32 s56, s1, 31
	s_lshr_b32 s1, s1, 1
	s_add_i32 s1, s1, s56
	s_lshl_b32 s62, s2, 5
	s_mul_i32 s1, s1, 12
	v_lshl_add_u64 v[2:3], s[62:63], 2, v[166:167]
	s_max_i32 s2, s33, 0
	s_sub_i32 s56, s0, s1
	s_cmp_lg_u32 s84, 0
	s_cbranch_scc1 .Lcl_6
	global_load_lds_dword v[2:3], off
.Lcl_6:
	v_mad_u64_u32 v[2:3], s[0:1], v168, s2, 0
	s_mulk_i32 s56, 0x2800
	s_add_i32 s0, s56, 0
	v_lshl_add_u64 v[2:3], v[2:3], 1, v[172:173]
	s_add_i32 m0, s0, s84
	s_add_i32 s0, s0, s85
	global_load_lds_dwordx4 v[2:3], off nt
	s_add_i32 m0, s0, 0x2000
	s_max_i32 s0, s33, 1
	s_lshl_b32 s62, s2, 5
	s_add_i32 s2, s0, -1
	s_add_i32 s0, s33, 0x77
	s_mul_hi_i32 s1, s0, 0x2aaaaaab
	s_lshr_b32 s56, s1, 31
	s_lshr_b32 s1, s1, 1
	s_add_i32 s1, s1, s56
	s_mul_i32 s1, s1, 12
	v_lshl_add_u64 v[2:3], s[62:63], 2, v[166:167]
	s_sub_i32 s56, s0, s1
	s_cmp_lg_u32 s84, 0
	s_cbranch_scc1 .Lcl_7
	global_load_lds_dword v[2:3], off
.Lcl_7:
	v_mad_u64_u32 v[2:3], s[0:1], v168, s2, 0
	s_mulk_i32 s56, 0x2800
	s_add_i32 s0, s56, 0
	v_lshl_add_u64 v[2:3], v[2:3], 1, v[172:173]
	s_add_i32 m0, s0, s84
	s_add_i32 s0, s0, s85
	global_load_lds_dwordx4 v[2:3], off nt
	s_add_i32 m0, s0, 0x2000
	s_max_i32 s0, s33, 2
	s_lshl_b32 s62, s2, 5
	s_add_i32 s2, s0, -2
	s_add_i32 s0, s33, 0x76
	s_mul_hi_i32 s1, s0, 0x2aaaaaab
	s_lshr_b32 s56, s1, 31
	s_lshr_b32 s1, s1, 1
	s_add_i32 s1, s1, s56
	s_mul_i32 s1, s1, 12
	v_lshl_add_u64 v[2:3], s[62:63], 2, v[166:167]
	s_sub_i32 s56, s0, s1
	s_cmp_lg_u32 s84, 0
	s_cbranch_scc1 .Lcl_8
	global_load_lds_dword v[2:3], off
.Lcl_8:
	v_mad_u64_u32 v[2:3], s[0:1], v168, s2, 0
	s_mulk_i32 s56, 0x2800
	s_add_i32 s0, s56, 0
	v_lshl_add_u64 v[2:3], v[2:3], 1, v[172:173]
	s_add_i32 m0, s0, s84
	s_add_i32 s0, s0, s85
	global_load_lds_dwordx4 v[2:3], off nt
	s_add_i32 m0, s0, 0x2000
	s_max_i32 s0, s33, 3
	s_lshl_b32 s62, s2, 5
	s_add_i32 s2, s0, -3
	s_add_i32 s0, s33, 0x75
	s_mul_hi_i32 s1, s0, 0x2aaaaaab
	s_lshr_b32 s56, s1, 31
	s_lshr_b32 s1, s1, 1
	s_add_i32 s1, s1, s56
	s_mul_i32 s1, s1, 12
	v_lshl_add_u64 v[2:3], s[62:63], 2, v[166:167]
	s_sub_i32 s56, s0, s1
	s_cmp_lg_u32 s84, 0
	s_cbranch_scc1 .Lcl_9
	global_load_lds_dword v[2:3], off
.Lcl_9:
	v_mad_u64_u32 v[2:3], s[0:1], v168, s2, 0
	s_mulk_i32 s56, 0x2800
	s_add_i32 s0, s56, 0
	v_lshl_add_u64 v[2:3], v[2:3], 1, v[172:173]
	s_add_i32 m0, s0, s84
	s_lshl_b32 s62, s2, 5
	s_add_i32 s0, s0, s85
	global_load_lds_dwordx4 v[2:3], off nt
	v_lshl_add_u64 v[2:3], s[62:63], 2, v[166:167]
	s_add_i32 m0, s0, 0x2000
	s_cmp_lg_u32 s84, 0
	s_cbranch_scc1 .Lcl_10
	global_load_lds_dword v[2:3], off
.Lcl_10:
	s_cmp_lg_u32 s84, 0
	s_cbranch_scc1 .Lclw_0
	s_waitcnt vmcnt(6)
	s_branch .Lclx_0
.Lclw_0:
	s_waitcnt vmcnt(3)
.Lclx_0:
	s_cmp_gt_i32 s5, -1
	s_waitcnt lgkmcnt(0)
	s_barrier
	s_cbranch_scc0 .LBB0_744
	s_max_i32 s0, s33, 4
	s_addk_i32 s33, 0x74
	s_add_i32 s2, s0, -4
	s_mul_hi_i32 s0, s33, 0x2aaaaaab
	s_lshr_b32 s1, s0, 31
	s_lshr_b32 s0, s0, 1
	s_add_i32 s0, s0, s1
	s_mul_i32 s0, s0, 12
	s_sub_i32 s33, s33, s0
	v_mad_u64_u32 v[2:3], s[0:1], v168, s2, 0
	s_mulk_i32 s33, 0x2800
	s_add_i32 s0, s33, 0
	v_lshl_add_u64 v[2:3], v[2:3], 1, v[172:173]
	s_add_i32 m0, s0, s84
	s_lshl_b32 s62, s2, 5
	s_add_i32 s0, s0, s85
	global_load_lds_dwordx4 v[2:3], off nt
	v_lshl_add_u64 v[2:3], s[62:63], 2, v[166:167]
	s_add_i32 m0, s0, 0x2000
	v_add_u32_e32 v4, 0x78, v88
	s_cmp_lg_u32 s84, 0
	s_cbranch_scc1 .Lcl_11
	global_load_lds_dword v[2:3], off
; #define MFMA32(a, b, c) __builtin_amdgcn_mfma_f32_32x32x16_bf16((a), (b), (c), 0, 0, 0)
; DI void fox_attn_blk(const Params& P, unsigned char* lds, LAS unsigned char* ldsl, int tid, int G, float PRUNE, int pir) {
;     ...
;                 const unsigned char* tb = lds + ((kt + 120) % 12) * 10240;
;                 const float off = it == 0 ? 0.f : __int_as_float(__builtin_amdgcn_readlane(__float_as_int(offv), it - 1));
;                 bf16x8 kf[4]; f32x4 ck[4];
; #pragma unroll
;                 for (int ks = 0; ks < 4; ++ks) kf[ks] = *(const bf16x8*)(tb + koff + (((2 * ks + hi) ^ ksw) << 4));
; #pragma unroll
;                 for (int blk = 0; blk < 2; ++blk)
; #pragma unroll
;                     for (int s = 0; s < 2; ++s) vf[blk][s] = *(const bf16x8*)(tb + voff + blk * 2048 + (((2 * s + hi) ^ vsw) << 4));
; #pragma unroll
;                 for (int s = 0; s < 2; ++s) { ck[2 * s] = *(const f32x4*)(tb + 8192 + wvu * 256 + (16 * s + 8 * hi) * 4); ck[2 * s + 1] = *(const f32x4*)(tb + 8192 + wvu * 256 + (16 * s + 8 * hi) * 4 + 16); }
;                 const float cb = cq + off;
; #pragma unroll
;                 for (int i = 0; i < 16; ++i) sc[i] = cb;
; #pragma unroll
;                 for (int ks = 0; ks < 4; ++ks) sc = MFMA32(kf[ks], qf[ks], sc);
;                 float mx = -INFINITY;
; #pragma unroll
;                 for (int r = 0; r < 16; ++r) { const int kl = 16 * (r >> 3) + 8 * hi + (r & 7);
;                     float v = sc[r] - ck[r >> 2][r & 3];
;                     if (kt == qb && kl > r32) v = -INFINITY;
;                     sc[r] = v; mx = fmaxf(mx, v); }
;                 { const auto rr = __builtin_amdgcn_permlane32_swap(__float_as_uint(mx), __float_as_uint(mx), false, false);
;                   mx = fmaxf(__uint_as_float(rr[0]), __uint_as_float(rr[1])); }
;                 const float mnew = fmaxf(mrun, mx); alpha = __builtin_amdgcn_exp2f(mrun - mnew); mrun = mnew;
; #pragma unroll
;                 for (int r = 0; r < 16; ++r) sc[r] = __builtin_amdgcn_exp2f(sc[r] - mnew);
;                 if (stag) pend = true; else ATT_TAIL();
.Lcl_11:
	v_mul_hi_i32 v2, v4, s89
	v_lshrrev_b32_e32 v3, 31, v2
	v_lshrrev_b32_e32 v2, 1, v2
	v_add_u32_e32 v2, v2, v3
	v_mul_lo_u32 v2, v2, 12
	v_sub_u32_e32 v2, v4, v2
	v_mad_i32_i24 v26, v2, s90, 0
	v_add_u32_e32 v27, v26, v169
	v_add_u32_e32 v2, v27, v214
	v_add_u32_e32 v3, v27, v215
	ds_read_b128 v[18:21], v2
	ds_read_b128 v[22:25], v3
	v_add_f32_e32 v2, 0, v90
	v_mov_b32_e32 v3, v2
	v_mov_b32_e32 v4, v2
	v_mov_b32_e32 v5, v2
	v_mov_b32_e32 v6, v2
	v_mov_b32_e32 v7, v2
	v_mov_b32_e32 v8, v2
	v_mov_b32_e32 v9, v2
	v_mov_b32_e32 v10, v2
	v_mov_b32_e32 v11, v2
	v_mov_b32_e32 v12, v2
	v_mov_b32_e32 v13, v2
	v_mov_b32_e32 v14, v2
	v_mov_b32_e32 v15, v2
	v_mov_b32_e32 v16, v2
	v_mov_b32_e32 v17, v2
	v_add_u32_e32 v34, v26, v207
	s_andn2_b64 vcc, exec, s[38:39]
	s_waitcnt lgkmcnt(0)
	v_mfma_f32_32x32x16_bf16 v[2:17], v[18:21], v[50:53], v[2:17]
	v_add_u32_e32 v18, v27, v216
	ds_read_b128 v[18:21], v18
	v_mfma_f32_32x32x16_bf16 v[2:17], v[22:25], v[54:57], v[2:17]
	v_add_u32_e32 v22, v27, v217
	ds_read_b128 v[22:25], v22
	v_add_u32_e32 v27, v26, v196
	v_add_u32_e32 v28, v27, v218
	v_add_u32_e32 v27, v27, v219
	ds_read_b128 v[74:77], v28 offset:4096
	ds_read_b128 v[70:73], v28 offset:6144
	ds_read_b128 v[78:81], v27 offset:4096
	ds_read_b128 v[66:69], v27 offset:6144
	s_waitcnt lgkmcnt(0)
	v_mfma_f32_32x32x16_bf16 v[2:17], v[18:21], v[58:61], v[2:17]
	ds_read_b128 v[18:21], v34 offset:8192
	ds_read_b128 v[26:29], v34 offset:8208
	ds_read_b128 v[30:33], v34 offset:8256
	ds_read_b128 v[34:37], v34 offset:8272
	v_mfma_f32_32x32x16_bf16 v[2:17], v[22:25], v[62:65], v[2:17]
	s_waitcnt lgkmcnt(0)
	s_nop 10
	v_sub_f32_e32 v2, v2, v18
	v_sub_f32_e32 v3, v3, v19
	v_cndmask_b32_e64 v2, v2, v223, s[40:41]
	v_cndmask_b32_e64 v3, v223, v3, s[42:43]
	v_sub_f32_e32 v4, v4, v20
	v_sub_f32_e32 v5, v5, v21
	v_max3_f32 v18, v2, s88, v3
	v_cndmask_b32_e64 v4, v4, v223, s[44:45]
	v_cndmask_b32_e64 v5, v5, v223, s[26:27]
	v_sub_f32_e32 v6, v6, v26
	v_sub_f32_e32 v7, v7, v27
	v_max3_f32 v18, v18, v4, v5
	v_cndmask_b32_e64 v6, v6, v223, s[28:29]
	v_cndmask_b32_e64 v7, v7, v223, s[30:31]
	v_sub_f32_e32 v8, v8, v28
	v_sub_f32_e32 v9, v9, v29
	v_max3_f32 v18, v18, v6, v7
	v_cndmask_b32_e64 v8, v8, v223, s[34:35]
	v_cndmask_b32_e64 v9, v9, v223, s[74:75]
	v_sub_f32_e32 v10, v10, v30
	v_sub_f32_e32 v11, v11, v31
	v_max3_f32 v18, v18, v8, v9
	v_cndmask_b32_e64 v10, v10, v223, s[76:77]
	v_cndmask_b32_e64 v11, v11, v223, s[82:83]
	v_sub_f32_e32 v12, v12, v32
	v_sub_f32_e32 v13, v13, v33
	v_max3_f32 v18, v18, v10, v11
	v_cndmask_b32_e64 v12, v12, v223, s[70:71]
	v_cndmask_b32_e64 v13, v13, v223, s[78:79]
	v_sub_f32_e32 v14, v14, v34
	v_sub_f32_e32 v15, v15, v35
	v_max3_f32 v18, v18, v12, v13
	v_cndmask_b32_e64 v14, v14, v223, s[20:21]
	v_cndmask_b32_e64 v15, v15, v223, s[22:23]
	v_sub_f32_e32 v16, v16, v36
	v_sub_f32_e32 v17, v17, v37
	v_max3_f32 v18, v18, v14, v15
	v_cndmask_b32_e64 v16, v16, v223, s[24:25]
	v_cndmask_b32_e64 v17, v17, v223, s[52:53]
	v_max3_f32 v18, v18, v16, v17
	v_mov_b32_e32 v19, v18
	s_nop 1
	v_permlane32_swap_b32_e32 v18, v19
	v_max3_f32 v94, v18, v19, s88
	v_sub_f32_e32 v2, v2, v118
	v_exp_f32_e32 v92, v2
	v_sub_f32_e32 v2, v3, v118
	v_exp_f32_e32 v37, v2
	v_sub_f32_e32 v2, v4, v118
	v_exp_f32_e32 v40, v2
	v_sub_f32_e32 v2, v5, v118
	v_exp_f32_e32 v44, v2
	v_sub_f32_e32 v2, v6, v118
	v_exp_f32_e32 v38, v2
	v_sub_f32_e32 v2, v7, v118
	v_exp_f32_e32 v41, v2
	v_sub_f32_e32 v2, v8, v118
	v_exp_f32_e32 v45, v2
	v_sub_f32_e32 v2, v9, v118
	v_exp_f32_e32 v46, v2
	v_sub_f32_e32 v2, v10, v118
	v_exp_f32_e32 v47, v2
	v_sub_f32_e32 v2, v11, v118
	v_exp_f32_e32 v48, v2
	v_sub_f32_e32 v2, v12, v118
	v_exp_f32_e32 v49, v2
	v_sub_f32_e32 v2, v13, v118
	v_exp_f32_e32 v35, v2
	v_sub_f32_e32 v2, v14, v118
	v_exp_f32_e32 v36, v2
	v_sub_f32_e32 v2, v15, v118
	v_exp_f32_e32 v39, v2
	v_sub_f32_e32 v2, v16, v118
	v_sub_f32_e32 v18, 0xff800000, v94
	v_exp_f32_e32 v42, v2
	v_sub_f32_e32 v2, v17, v118
	v_exp_f32_e32 v43, v2
	v_exp_f32_e32 v34, v18
	v_cndmask_b32_e64 v2, 0, 1, s[38:39]
	v_cmp_ne_u32_e64 s[56:57], 1, v2
	s_cbranch_vccnz .LBB0_745
	v_add_f32_e32 v2, 0, v92
	v_add_f32_e32 v2, v37, v2
	v_add_f32_e32 v2, v40, v2
	v_add_f32_e32 v2, v44, v2
	v_add_f32_e32 v2, v38, v2
	v_add_f32_e32 v2, v41, v2
	v_add_f32_e32 v2, v45, v2
	v_add_f32_e32 v2, v46, v2
	v_add_f32_e32 v2, v47, v2
	v_add_f32_e32 v2, v48, v2
	v_add_f32_e32 v2, v49, v2
	v_add_f32_e32 v2, v35, v2
	v_add_f32_e32 v2, v36, v2
	v_add_f32_e32 v2, v39, v2
	v_cmp_neq_f32_e32 vcc, 1.0, v34
	v_add_f32_e32 v2, v42, v2
	s_cmp_lg_u64 vcc, 0
	v_add_f32_e32 v93, v43, v2
	v_mul_f32_e32 v2, 0, v34
	s_cselect_b64 vcc, -1, 0
	v_cndmask_b32_e32 v2, 0, v2, vcc
	v_cvt_pk_bf16_f32 v96, v92, v37
	v_cvt_pk_bf16_f32 v97, v40, v44
	v_cvt_pk_bf16_f32 v98, v38, v41
	v_cvt_pk_bf16_f32 v99, v45, v46
	v_mov_b32_e32 v3, v2
	v_mov_b32_e32 v4, v2
	v_mov_b32_e32 v5, v2
	v_mov_b32_e32 v6, v2
	v_mov_b32_e32 v7, v2
	v_mov_b32_e32 v8, v2
	v_mov_b32_e32 v9, v2
	v_mov_b32_e32 v10, v2
	v_mov_b32_e32 v11, v2
	v_mov_b32_e32 v12, v2
	v_mov_b32_e32 v13, v2
	v_mov_b32_e32 v14, v2
	v_mov_b32_e32 v15, v2
	v_mov_b32_e32 v16, v2
	v_mov_b32_e32 v17, v2
	v_cvt_pk_bf16_f32 v100, v47, v48
	v_cvt_pk_bf16_f32 v101, v49, v35
	v_mfma_f32_32x32x16_bf16 v[18:33], v[74:77], v[96:99], v[2:17]
	v_cvt_pk_bf16_f32 v102, v36, v39
	v_cvt_pk_bf16_f32 v103, v42, v43
	v_fmac_f32_e32 v93, 0, v34
	v_mfma_f32_32x32x16_bf16 v[2:17], v[70:73], v[96:99], v[2:17]
	v_mfma_f32_32x32x16_bf16 v[18:33], v[78:81], v[100:103], v[18:33]
	v_mfma_f32_32x32x16_bf16 v[2:17], v[66:69], v[100:103], v[2:17]
	s_branch .LBB0_746

; #define BLK_BAR() asm volatile("s_waitcnt lgkmcnt(0)\n\ts_barrier" ::: "memory")
; DI void fox_attn_blk(const Params& P, unsigned char* lds, LAS unsigned char* ldsl, int tid, int G, float PRUNE, int pir) {
;     ...
;         for (int it = 0; it <= nvmax; ++it) {
;     ...
;             asm volatile("s_waitcnt vmcnt(6)" ::: "memory");
;             BLK_BAR();
;         }
.Lclx_1:
	s_waitcnt lgkmcnt(0)
	s_barrier
	s_cmp_eq_u32 s5, 0
	s_cbranch_scc1 .LBB0_759
	s_mov_b32 s59, 0
	s_mov_b32 s33, s86
	s_mov_b64 s[0:1], s[36:37]
	s_andn2_b64 vcc, exec, s[0:1]
	s_cbranch_vccnz .LBB0_751

; #define MFMA32(a, b, c) __builtin_amdgcn_mfma_f32_32x32x16_bf16((a), (b), (c), 0, 0, 0)
; DI void fox_attn_blk(const Params& P, unsigned char* lds, LAS unsigned char* ldsl, int tid, int G, float PRUNE, int pir) {
;     ...
;         for (int it = 0; it <= nvmax; ++it) {
;             if (pend) { ATT_TAIL(); pend = false; }
;             DMA_TILE(QB0 - it - 4);
;             const int kt = qb - it;
;             if (it <= nvalid) {
;                 const unsigned char* tb = lds + ((kt + 120) % 12) * 10240;
;                 const float off = it == 0 ? 0.f : __int_as_float(__builtin_amdgcn_readlane(__float_as_int(offv), it - 1));
;                 bf16x8 kf[4]; f32x4 ck[4];
; #pragma unroll
;                 for (int ks = 0; ks < 4; ++ks) kf[ks] = *(const bf16x8*)(tb + koff + (((2 * ks + hi) ^ ksw) << 4));
; #pragma unroll
;                 for (int blk = 0; blk < 2; ++blk)
; #pragma unroll
;                     for (int s = 0; s < 2; ++s) vf[blk][s] = *(const bf16x8*)(tb + voff + blk * 2048 + (((2 * s + hi) ^ vsw) << 4));
; #pragma unroll
;                 for (int s = 0; s < 2; ++s) { ck[2 * s] = *(const f32x4*)(tb + 8192 + wvu * 256 + (16 * s + 8 * hi) * 4); ck[2 * s + 1] = *(const f32x4*)(tb + 8192 + wvu * 256 + (16 * s + 8 * hi) * 4 + 16); }
;                 const float cb = cq + off;
; #pragma unroll
;                 for (int i = 0; i < 16; ++i) sc[i] = cb;
; #pragma unroll
;                 for (int ks = 0; ks < 4; ++ks) sc = MFMA32(kf[ks], qf[ks], sc);
;                 float mx = -INFINITY;
; #pragma unroll
;                 for (int r = 0; r < 16; ++r) { const int kl = 16 * (r >> 3) + 8 * hi + (r & 7);
;                     float v = sc[r] - ck[r >> 2][r & 3];
;                     if (kt == qb && kl > r32) v = -INFINITY;
;                     sc[r] = v; mx = fmaxf(mx, v); }
;                 { const auto rr = __builtin_amdgcn_permlane32_swap(__float_as_uint(mx), __float_as_uint(mx), false, false);
;                   mx = fmaxf(__uint_as_float(rr[0]), __uint_as_float(rr[1])); }
;                 const float mnew = fmaxf(mrun, mx); alpha = __builtin_amdgcn_exp2f(mrun - mnew); mrun = mnew;
; #pragma unroll
;                 for (int r = 0; r < 16; ++r) sc[r] = __builtin_amdgcn_exp2f(sc[r] - mnew);
;                 if (stag) pend = true; else ATT_TAIL();
.LBB0_751:
	s_add_i32 s0, s33, 0xffffff8c
	s_max_i32 s0, s0, 4
	s_add_i32 s2, s0, -4
	s_mul_hi_i32 s0, s33, 0x2aaaaaab
	s_lshr_b32 s1, s0, 31
	s_lshr_b32 s0, s0, 1
	s_add_i32 s0, s0, s1
	s_mul_i32 s0, s0, 12
	s_sub_i32 s58, s33, s0
	v_mad_u64_u32 v[96:97], s[0:1], v168, s2, 0
	s_mulk_i32 s58, 0x2800
	s_add_i32 s0, s58, 0
	v_lshl_add_u64 v[96:97], v[96:97], 1, v[172:173]
	s_add_i32 m0, s0, s84
	s_lshl_b32 s62, s2, 5
	s_add_i32 s0, s0, s85
	global_load_lds_dwordx4 v[96:97], off nt
	v_lshl_add_u64 v[96:97], s[62:63], 2, v[166:167]
	s_add_i32 m0, s0, 0x2000
	s_add_i32 s58, s59, 1
	s_cmp_lg_u32 s84, 0
	s_cbranch_scc1 .Lcl_12
	global_load_lds_dword v[96:97], off
.Lcl_12:
	s_cmp_gt_u32 s58, s4
	s_mov_b64 s[0:1], 0
	s_cbranch_scc1 .LBB0_756
	v_add3_u32 v34, v1, s33, 4
	v_mul_hi_i32 v35, v34, s89
	v_lshrrev_b32_e32 v36, 31, v35
	v_lshrrev_b32_e32 v35, 1, v35
	v_add_u32_e32 v35, v35, v36
	v_mul_lo_u32 v35, v35, 12
	v_sub_u32_e32 v34, v34, v35
	v_mad_i32_i24 v92, v34, s90, 0
	v_add_u32_e32 v74, v92, v169
	v_add_u32_e32 v34, v74, v214
	s_add_i32 s0, s59, 64
	v_add_u32_e32 v35, v74, v215
	v_add_u32_e32 v36, v74, v216
	v_add_u32_e32 v37, v74, v217
	v_add_u32_e32 v38, v92, v196
	v_add_u32_e32 v117, v92, v207
	v_add_u32_e32 v39, v38, v218
	v_add_u32_e32 v95, v38, v219
	ds_read_b128 v[120:123], v34
	ds_read_b128 v[124:127], v35
	ds_read_b128 v[100:103], v117 offset:8192
	ds_read_b128 v[104:107], v117 offset:8208
	ds_read_b128 v[108:111], v117 offset:8256
	ds_read_b128 v[112:115], v117 offset:8272
	ds_read_b128 v[66:69], v36
	ds_read_b128 v[96:99], v37
	ds_read_b128 v[74:77], v39 offset:4096
	ds_read_b128 v[70:73], v39 offset:6144
	ds_read_b128 v[78:81], v95 offset:4096
	v_readlane_b32 s0, v91, s0
	s_and_b64 vcc, exec, s[56:57]
	s_nop 0
	v_add_f32_e32 v116, s0, v90
	v_sub_f32_e32 v116, v116, v118
	s_mov_b64 s[0:1], -1
	s_waitcnt lgkmcnt(5)
	v_sub_f32_e32 v34, v116, v100
	v_sub_f32_e32 v35, v116, v101
	v_sub_f32_e32 v36, v116, v102
	v_sub_f32_e32 v37, v116, v103
	v_sub_f32_e32 v38, v116, v104
	v_sub_f32_e32 v39, v116, v105
	v_sub_f32_e32 v40, v116, v106
	v_sub_f32_e32 v41, v116, v107
	v_sub_f32_e32 v42, v116, v108
	v_sub_f32_e32 v43, v116, v109
	v_sub_f32_e32 v44, v116, v110
	v_sub_f32_e32 v45, v116, v111
	v_sub_f32_e32 v46, v116, v112
	v_sub_f32_e32 v47, v116, v113
	v_sub_f32_e32 v48, v116, v114
	v_sub_f32_e32 v49, v116, v115
	s_nop 1
	v_mfma_f32_32x32x16_bf16 v[34:49], v[120:123], v[50:53], v[34:49]
	v_mfma_f32_32x32x16_bf16 v[34:49], v[124:127], v[54:57], v[34:49]
	s_waitcnt lgkmcnt(3)
	v_mfma_f32_32x32x16_bf16 v[34:49], v[66:69], v[58:61], v[34:49]
	ds_read_b128 v[66:69], v95 offset:6144
	v_mfma_f32_32x32x16_bf16 v[34:49], v[96:99], v[62:65], v[34:49]
	s_waitcnt lgkmcnt(0)
	s_nop 10
	v_exp_f32_e32 v92, v34
	v_exp_f32_e32 v34, v35
	v_exp_f32_e32 v35, v45
	v_exp_f32_e32 v45, v40
	v_exp_f32_e32 v40, v36
	v_exp_f32_e32 v36, v46
	v_exp_f32_e32 v46, v41
	v_exp_f32_e32 v41, v39
	v_exp_f32_e32 v39, v47
	v_exp_f32_e32 v47, v42
	v_exp_f32_e32 v42, v48
	v_exp_f32_e32 v48, v43
	v_exp_f32_e32 v43, v49
	v_exp_f32_e32 v49, v44
	v_exp_f32_e32 v44, v37
	v_exp_f32_e32 v38, v38
	v_mov_b32_e32 v37, v34
	v_mov_b32_e32 v34, 1.0
	s_cbranch_vccnz .LBB0_757
	v_cmp_neq_f32_e32 vcc, 1.0, v34
	s_cbranch_vccz .LBB0_755
	v_pk_mul_f32 v[16:17], v[16:17], v[34:35] op_sel_hi:[1,0]
	v_pk_mul_f32 v[14:15], v[14:15], v[34:35] op_sel_hi:[1,0]
	v_pk_mul_f32 v[12:13], v[12:13], v[34:35] op_sel_hi:[1,0]
	v_pk_mul_f32 v[10:11], v[10:11], v[34:35] op_sel_hi:[1,0]
	v_pk_mul_f32 v[8:9], v[8:9], v[34:35] op_sel_hi:[1,0]
	v_pk_mul_f32 v[6:7], v[6:7], v[34:35] op_sel_hi:[1,0]
	v_pk_mul_f32 v[4:5], v[4:5], v[34:35] op_sel_hi:[1,0]
	v_pk_mul_f32 v[2:3], v[2:3], v[34:35] op_sel_hi:[1,0]
	v_pk_mul_f32 v[32:33], v[32:33], v[34:35] op_sel_hi:[1,0]
	v_pk_mul_f32 v[30:31], v[30:31], v[34:35] op_sel_hi:[1,0]
	v_pk_mul_f32 v[28:29], v[28:29], v[34:35] op_sel_hi:[1,0]
	v_pk_mul_f32 v[26:27], v[26:27], v[34:35] op_sel_hi:[1,0]
	v_pk_mul_f32 v[24:25], v[24:25], v[34:35] op_sel_hi:[1,0]
	v_pk_mul_f32 v[22:23], v[22:23], v[34:35] op_sel_hi:[1,0]
	v_pk_mul_f32 v[20:21], v[20:21], v[34:35] op_sel_hi:[1,0]
	v_pk_mul_f32 v[18:19], v[18:19], v[34:35] op_sel_hi:[1,0]

; #define BLK_BAR() asm volatile("s_waitcnt lgkmcnt(0)\n\ts_barrier" ::: "memory")
; DI void fox_attn_blk(const Params& P, unsigned char* lds, LAS unsigned char* ldsl, int tid, int G, float PRUNE, int pir) {
;     ...
;             asm volatile("s_waitcnt vmcnt(6)" ::: "memory");
;             BLK_BAR();
;         }
.Lclx_2:
	s_waitcnt lgkmcnt(0)
	s_barrier
	s_add_i32 s33, s33, -1
	s_cmp_eq_u32 s5, s58
	s_cbranch_scc1 .LBB0_760
	s_mov_b32 s59, s58
	v_mov_b32_e32 v94, v95
	s_andn2_b64 vcc, exec, s[0:1]
	s_cbranch_vccz .LBB0_748
	s_branch .LBB0_751
